# layer-1 weight transposes moved from the layer-0 out-proj phase into the layer-0 PEER gather phase (first-half workgroups before their tokens, second-half after), where the partner's vector-bound gath
# baseline (speedup 1.0000x reference)
; DEV int opaque_tid() { int t = (int)threadIdx.x; asm volatile("" : "+v"(t)); return t; }
; __device__ void peer_gather_phase(const Params& P, int l, bool do_store) {
;   const int lane = opaque_tid() & 63, w = opaque_tid() >> 6;
;   const unsigned char* U = P.U8 + (size_t)l * 16384 * 768 + (lane & 31) * 24;
;   const unsigned char* V = P.V8 + (size_t)l * 16384 * 512 + lane * 8;
;   const float* SU = P.SU + l * 16384;
;   const float* SV = P.SV + l * 16384;
;   int nev0, nev1; float ngv0, ngv1; uint4 nxa, nxc;
;   {
;     const int t = blockIdx.x * 4 + w;
;     nev0 = P.EXP[(size_t)t * 128 + lane]; nev1 = P.EXP[(size_t)t * 128 + 64 + lane];
;     ngv0 = P.GATE[(size_t)t * 128 + lane]; ngv1 = P.GATE[(size_t)t * 128 + 64 + lane];
;     const bf16_t* xb = P.XB + (size_t)t * 1024 + lane * 16;
;     nxa = *(const uint4*)xb; nxc = *(const uint4*)(xb + 8);
;   }
; __device__ void run_phase(const Params& P, int ph, char* smem, bool do_store) {
;     ...
;       const bool tr_first = ((bid >> 8) & 1) == 0;
;       const size_t gtid = (size_t)bid * 256 + opaque_tid(), gsz = (size_t)G * 256;
;       if (l == 0 && tr_first) weight_transposes(P, 1, gtid, gsz);
;       gemm_phase256<1>(P, l, P.CAT, P.WoutT + (size_t)l * 1024 * 1024, 8, smem);
;       if (l == 0 && !tr_first) weight_transposes(P, 1, gtid, gsz);
.LBB0_14:
	v_readlane_b32 s4, v248, 27
	s_add_i32 s4, s4, 1
	v_readlane_b32 s2, v249, 37
	s_cmp_eq_u32 s4, s2
	v_writelane_b32 v248, s4, 27
	s_cselect_b64 s[4:5], -1, 0
	v_writelane_b32 v248, s4, 32
	s_mov_b64 s[0:1], -1
	s_nop 0
	v_writelane_b32 v248, s5, 33
	v_readlane_b32 s4, v249, 38
	v_readlane_b32 s5, v249, 39
	s_and_b64 vcc, exec, s[4:5]
	s_cbranch_vccz .LBB0_310
	v_readlane_b32 s0, v251, 58
	v_readlane_b32 s1, v251, 59
	s_load_dword s0, s[0:1], 0x0
	s_waitcnt lgkmcnt(0)
	v_writelane_b32 v248, s0, 34
	s_nop 1
	v_writelane_b32 v248, s1, 35
	v_readlane_b32 s0, v249, 40
	s_cmp_lt_i32 s0, 4
	s_mov_b64 s[0:1], -1
	s_cbranch_scc1 .LBB0_65
	v_readlane_b32 s0, v249, 40
	s_cmp_lt_i32 s0, 6
	s_mov_b64 s[0:1], -1
	s_cbranch_scc1 .LBB0_39
	v_readlane_b32 s0, v249, 40
	s_cmp_gt_i32 s0, 6
	s_cbranch_scc0 .LBB0_38
	v_readlane_b32 s0, v251, 60
	v_readlane_b32 s1, v251, 61
	v_mov_b32_e32 v0, v202
	v_mov_b32_e32 v1, v202
	s_andn2_b64 vcc, exec, s[0:1]
	s_cbranch_vccnz .LBB0_38
	v_readlane_b32 s0, v248, 3
	v_readlane_b32 s1, v248, 4
	s_nop 0
	s_and_b64 vcc, exec, s[0:1]
	s_cbranch_vccz .Lgather_resume
	v_mov_b32_e32 v182, v202
	v_readlane_b32 s0, v252, 4
	v_readlane_b32 s1, v252, 5
	v_ashrrev_i32_e32 v183, 31, v182
	s_nop 0
	v_lshl_add_u64 v[180:181], s[0:1], 0, v[182:183]
	v_readlane_b32 s0, v248, 34
	s_mov_b32 s4, s0
	s_ashr_i32 s5, s0, 31
	s_lshl_b64 s[38:39], s[4:5], 8
	s_movk_i32 s65, 0x2000
	s_movk_i32 s97, 0x4000
	v_readlane_b32 s98, v249, 19
	v_readlane_b32 s99, v249, 20
	s_mov_b64 s[0:1], 0x4c000
	v_cmp_gt_u64_e64 s[0:1], s[0:1], v[180:181]
	s_branch .Ltr_A_body
.Lgather_resume:
	v_mov_b32_e32 v0, v202
	v_mov_b32_e32 v1, v202
	v_ashrrev_i32_e32 v73, 6, v1
	v_and_b32_e32 v1, 31, v0
	v_readlane_b32 s0, v249, 41
	v_mul_u32_u24_e32 v176, 24, v1
	v_readlane_b32 s1, v249, 42
	v_and_b32_e32 v72, 63, v0
	v_readlane_b32 s4, v251, 2
	v_lshl_add_u64 v[74:75], s[0:1], 0, v[176:177]
	v_readlane_b32 s0, v249, 43
	v_lshlrev_b32_e32 v176, 3, v72
	v_readlane_b32 s1, v249, 44
	v_readlane_b32 s5, v251, 3
	v_readlane_b32 s6, v251, 4
	v_lshl_add_u64 v[76:77], s[0:1], 0, v[176:177]
	v_readlane_b32 s0, v251, 62
	v_lshlrev_b32_e32 v176, 5, v72
	v_readlane_b32 s7, v251, 5
	v_add_u32_e32 v2, s0, v73
	v_ashrrev_i32_e32 v3, 31, v2
	v_lshlrev_b64 v[4:5], 11, v[2:3]
	v_lshl_add_u64 v[4:5], s[28:29], 0, v[4:5]
	v_lshlrev_b64 v[2:3], 9, v[2:3]
	v_lshl_add_u64 v[4:5], v[4:5], 0, v[176:177]
	v_lshl_or_b32 v2, v72, 2, v2
	global_load_dwordx4 v[64:67], v[4:5], off offset:16
	global_load_dwordx4 v[68:71], v[4:5], off
	v_lshl_add_u64 v[4:5], s[4:5], 0, v[2:3]
	v_lshl_add_u64 v[2:3], s[6:7], 0, v[2:3]
	global_load_dword v93, v[4:5], off offset:256
	global_load_dword v91, v[4:5], off
	global_load_dword v188, v[2:3], off offset:256
	global_load_dword v179, v[2:3], off
	v_readlane_b32 s0, v249, 49
	v_readlane_b32 s4, v248, 32
	v_readlane_b32 s1, v249, 50
	v_readlane_b32 s5, v248, 33
	s_and_b64 s[38:39], s[0:1], s[4:5]
	v_readlane_b32 s0, v248, 1
	v_readlane_b32 s1, v248, 2
	s_and_b64 s[0:1], s[0:1], s[4:5]
	s_xor_b64 s[0:1], s[0:1], -1
	v_writelane_b32 v248, s0, 45
	v_lshl_add_u64 v[78:79], s[28:29], 0, v[176:177]
	v_lshlrev_b32_e32 v176, 6, v72
	v_writelane_b32 v248, s1, 46
	v_readlane_b32 s0, v249, 54
	v_readlane_b32 s1, v249, 55
	v_lshlrev_b32_e32 v0, 5, v0
	v_readlane_b32 s44, v252, 12
	v_lshl_add_u64 v[82:83], s[0:1], 0, v[176:177]
	v_readlane_b32 s0, v249, 56
	v_readlane_b32 s1, v249, 57
	v_lshlrev_b32_e32 v2, 4, v72
	v_and_b32_e32 v0, 0x3e0, v0
	v_readlane_b32 s58, v252, 26
	v_readlane_b32 s59, v252, 27
	v_lshl_add_u64 v[84:85], s[0:1], 0, v[176:177]
	v_readlane_b32 s0, v249, 5
	v_cmp_lt_u32_e64 s[40:41], 31, v72
	v_lshl_add_u64 v[80:81], s[58:59], 0, v[176:177]
	v_lshlrev_b32_e32 v86, 1, v0
	v_lshlrev_b32_e32 v176, 1, v2
	v_mov_b32_e32 v87, v177
	s_mov_b32 s2, s0
	s_movk_i32 s33, 0x300
	v_readlane_b32 s45, v252, 13
	v_readlane_b32 s46, v252, 14
	v_readlane_b32 s47, v252, 15
	v_readlane_b32 s48, v252, 16
	v_readlane_b32 s49, v252, 17
	v_readlane_b32 s50, v252, 18
	v_readlane_b32 s51, v252, 19
	v_readlane_b32 s52, v252, 20
	v_readlane_b32 s53, v252, 21
	v_readlane_b32 s54, v252, 22
	v_readlane_b32 s55, v252, 23
	v_readlane_b32 s56, v252, 24
	v_readlane_b32 s57, v252, 25
	v_readlane_b32 s1, v249, 6
	v_lshrrev_b32_e32 v74, 5, v72
	v_lshlrev_b32_e32 v74, 2, v74
	v_lshl_add_u32 v74, v73, 9, v74
	v_lshlrev_b32_e32 v75, 2, v72
	v_lshl_add_u32 v75, v73, 9, v75
	s_waitcnt vmcnt(0)
	s_branch .LBB0_21

; DEV int opaque_tid() { int t = (int)threadIdx.x; asm volatile("" : "+v"(t)); return t; }
; __device__ void run_phase(const Params& P, int ph, char* smem, bool do_store) {
;     ...
;       const bool tr_first = ((bid >> 8) & 1) == 0;
;       const size_t gtid = (size_t)bid * 256 + opaque_tid(), gsz = (size_t)G * 256;
;       if (l == 0 && tr_first) weight_transposes(P, 1, gtid, gsz);
;       gemm_phase256<1>(P, l, P.CAT, P.WoutT + (size_t)l * 1024 * 1024, 8, smem);
;       if (l == 0 && !tr_first) weight_transposes(P, 1, gtid, gsz);
.LBB0_37:
	v_readlane_b32 s0, v252, 2
	v_readlane_b32 s1, v252, 3
	v_readlane_b32 s4, v248, 1
	v_readlane_b32 s5, v248, 2
	s_andn2_b64 s[0:1], s[4:5], s[0:1]
	s_and_b64 vcc, exec, s[0:1]
	s_cbranch_vccz .Lgather_exit_resume
	v_mov_b32_e32 v182, v202
	v_readlane_b32 s0, v252, 4
	v_readlane_b32 s1, v252, 5
	v_ashrrev_i32_e32 v183, 31, v182
	s_nop 0
	v_lshl_add_u64 v[180:181], s[0:1], 0, v[182:183]
	v_readlane_b32 s0, v248, 34
	s_mov_b32 s4, s0
	s_ashr_i32 s5, s0, 31
	s_lshl_b64 s[38:39], s[4:5], 8
	s_movk_i32 s65, 0x2000
	s_movk_i32 s97, 0x4000
	v_readlane_b32 s98, v249, 19
	v_readlane_b32 s99, v249, 20
	s_branch .Ltr_B_body

; DEV int opaque_tid() { int t = (int)threadIdx.x; asm volatile("" : "+v"(t)); return t; }
; __device__ void run_phase(const Params& P, int ph, char* smem, bool do_store) {
;     ...
;     case 3: {
;       const bool tr_first = ((bid >> 8) & 1) == 0;
;       const size_t gtid = (size_t)bid * 256 + opaque_tid(), gsz = (size_t)G * 256;
;       if (l == 0 && tr_first) weight_transposes(P, 1, gtid, gsz);
;       gemm_phase256<1>(P, l, P.CAT, P.WoutT + (size_t)l * 1024 * 1024, 8, smem);
;       if (l == 0 && !tr_first) weight_transposes(P, 1, gtid, gsz);
.LBB0_65:
	s_andn2_b64 vcc, exec, s[0:1]
	s_cbranch_vccnz .LBB0_309
	v_readlane_b32 s0, v249, 40
	s_cmp_lt_i32 s0, 2
	s_mov_b64 s[0:1], -1
	s_cbranch_scc1 .LBB0_222
	v_readlane_b32 s0, v249, 40
	s_cmp_gt_i32 s0, 2
	s_mov_b64 s[0:1], -1
	s_cbranch_scc0 .LBB0_144
	v_mov_b32_e32 v182, v202
	v_readlane_b32 s0, v252, 4
	v_readlane_b32 s1, v252, 5
	v_ashrrev_i32_e32 v183, 31, v182
	s_nop 0
	v_lshl_add_u64 v[180:181], s[0:1], 0, v[182:183]
	v_readlane_b32 s0, v248, 34
	v_readlane_b32 s1, v248, 35
	s_mov_b32 s4, s0
	s_ashr_i32 s5, s0, 31
	v_writelane_b32 v248, s0, 34
	s_lshl_b64 s[38:39], s[4:5], 8
	s_nop 0
	v_writelane_b32 v248, s1, 35
	s_nop 0
	v_readlane_b32 s0, v248, 3
	v_readlane_b32 s1, v248, 4
	s_andn2_b64 vcc, exec, s[0:1]
	s_mov_b64 s[0:1], 0x4c000
	v_cmp_gt_u64_e64 s[0:1], s[0:1], v[180:181]
	s_branch .LBB0_101
.Ltr_A_body:
	s_and_saveexec_b64 s[40:41], s[0:1]
	s_cbranch_execz .LBB0_88
	s_mov_b64 s[42:43], 0
	v_mov_b64_e32 v[0:1], v[180:181]
	s_branch .LBB0_72

; DEV int opaque_tid() { int t = (int)threadIdx.x; asm volatile("" : "+v"(t)); return t; }
; template <int EPI>
; __device__ void gemm_phase256(const Params& P, int l, const bf16_t* __restrict__ A, const bf16_t* __restrict__ Bt, int NT, char* smem) {
;   bf16_t* As = (bf16_t*)smem;
;   bf16_t* Bs = As + 256 * 72;
;   const int tid = opaque_tid(), lane = tid & 63, w = tid >> 6;
;   const int wm = w >> 1, wn = w & 1, lr = lane & 31, hk = lane >> 5;
;   const int xcd = blockIdx.x & 7, lb = blockIdx.x >> 3, nbx = ((int)gridDim.x - xcd + 7) >> 3;
;   const int nloc = 16 * NT;
;   for (int lt = lb; lt < nloc; lt += nbx) {
;     const int mtl = lt / NT, nt = lt - mtl * NT;
;     const int mt = xcd * 16 + mtl;
;     const int m0 = mt * 256, n0 = nt * 128;
;     f32x16 acc[4][2];
; #pragma unroll
;     for (int a = 0; a < 4; ++a)
; #pragma unroll
;       for (int b = 0; b < 2; ++b)
; #pragma unroll
;         for (int i = 0; i < 16; ++i) acc[a][b][i] = 0.f;
;     uint4 ra0, ra1, ra2, ra3, ra4, ra5, ra6, ra7, rb0, rb1, rb2, rb3;
;     const int lrow = tid >> 3, lc8 = (tid & 7) * 8;
;     const bf16_t* Ap = A + (size_t)(m0 + lrow) * 1024 + lc8;
;     const bf16_t* Bp = Bt + (size_t)(n0 + lrow) * 1024 + lc8;
; __device__ void run_phase(const Params& P, int ph, char* smem, bool do_store) {
;     ...
;       gemm_phase256<1>(P, l, P.CAT, P.WoutT + (size_t)l * 1024 * 1024, 8, smem);
.LBB0_101:
	v_readlane_b32 s0, v249, 40
	s_cmp_eq_u32 s0, 7
	s_cbranch_scc1 .Lgather_resume
	v_readlane_b32 s0, v252, 56
	v_readlane_b32 s1, v252, 57
	v_mov_b32_e32 v179, v202
	s_andn2_b64 vcc, exec, s[0:1]
	s_cbranch_vccnz .LBB0_108
	v_and_b32_e32 v0, 31, v179
	v_bfe_u32 v2, v179, 6, 1
	v_readlane_b32 s0, v251, 63
	v_readlane_b32 s4, v248, 34
	v_bfe_u32 v1, v179, 5, 1
	v_lshlrev_b32_e32 v3, 4, v179
	v_readlane_b32 s6, v248, 5
	v_lshl_or_b32 v6, v2, 6, v0
	v_and_b32_e32 v7, 0xfffff80, v179
	v_lshlrev_b32_e32 v2, 7, v2
	s_add_i32 s0, s4, s0
	v_ashrrev_i32_e32 v183, 3, v179
	v_and_b32_e32 v176, 0x70, v3
	v_readlane_b32 s7, v248, 6
	s_movk_i32 s4, 0x90
	v_lshlrev_b32_e32 v5, 4, v1
	v_lshl_or_b32 v1, v1, 2, v7
	v_lshl_or_b32 v0, v0, 1, v2
	s_ashr_i32 s2, s0, 3
	v_lshl_add_u64 v[184:185], s[30:31], 0, v[176:177]
	v_lshl_add_u64 v[186:187], s[6:7], 0, v[176:177]
	v_mad_u64_u32 v[188:189], s[0:1], v183, s4, v[176:177]
	v_and_b32_e32 v4, 0xfffff9f, v179
	v_and_b32_e32 v176, 0xf0, v3
	v_or_b32_e32 v3, 0x60, v179
	v_mad_u64_u32 v[190:191], s[0:1], v1, s67, v[0:1]
	v_readlane_b32 s40, v251, 42
	v_and_b32_e32 v0, 7, v179
	v_readlane_b32 s5, v248, 35
	v_mul_lo_u32 v2, v4, s4
	v_mul_lo_u32 v3, v3, s4
	v_mul_u32_u24_e32 v4, 0x90, v6
	v_readlane_b32 s42, v251, 44
	v_readlane_b32 s43, v251, 45
	v_lshlrev_b32_e32 v0, 4, v0
	v_mov_b32_e32 v1, v177
	v_readlane_b32 s0, v250, 62
	v_lshl_add_u64 v[192:193], s[42:43], 0, v[176:177]
	v_lshl_add_u64 v[194:195], s[6:7], 0, v[0:1]
	v_add_u32_e32 v189, s0, v183
	s_lshl_b32 s4, s2, 7
	v_add_u32_e32 v191, v5, v2
	v_add_u32_e32 v200, v5, v3
	v_add_u32_e32 v201, v5, v4
	v_readlane_b32 s5, v250, 61
	v_readlane_b32 s41, v251, 43
	v_readlane_b32 s44, v251, 46
	v_readlane_b32 s45, v251, 47
	v_readlane_b32 s46, v251, 48
	v_readlane_b32 s47, v251, 49
	v_readlane_b32 s48, v251, 50
	v_readlane_b32 s49, v251, 51
	v_readlane_b32 s50, v251, 52
	v_readlane_b32 s51, v251, 53
	v_readlane_b32 s52, v251, 54
	v_readlane_b32 s53, v251, 55
	v_readlane_b32 s54, v251, 56
	v_readlane_b32 s55, v251, 57

; __device__ void tr_job(const float* __restrict__ src, bf16_t* __restrict__ dst, int K, int Nsrc, int Npad, size_t gtid, size_t gsz) {
;   const size_t total = (size_t)Npad * (size_t)(K / 8);
;   for (size_t i = gtid; i < total; i += gsz) {
;     const int n = (int)(i % (size_t)Npad); const int k8 = (int)(i / (size_t)Npad);
; __device__ void run_phase(const Params& P, int ph, char* smem, bool do_store) {
;     ...
;       if (l == 0 && !tr_first) weight_transposes(P, 1, gtid, gsz);
.Ltr_B_body:
	s_mov_b64 s[0:1], 0x4c000
	v_cmp_gt_u64_e32 vcc, s[0:1], v[180:181]
	s_and_saveexec_b64 s[40:41], vcc
	s_cbranch_execz .LBB0_128
	s_mov_b64 s[42:43], 0
	v_mov_b64_e32 v[0:1], v[180:181]
	s_branch .LBB0_112

; __device__ void run_phase(const Params& P, int ph, char* smem, bool do_store) {
;     ...
;       if (l == 0 && tr_first) weight_transposes(P, 1, gtid, gsz);
;       gemm_phase256<1>(P, l, P.CAT, P.WoutT + (size_t)l * 1024 * 1024, 8, smem);
;       if (l == 0 && !tr_first) weight_transposes(P, 1, gtid, gsz);
;     } break;
.LBB0_142:
	s_or_b64 exec, exec, s[0:1]
	v_readlane_b32 s0, v249, 40
	s_cmp_eq_u32 s0, 7
	s_cbranch_scc1 .Lgather_exit_resume
